# passC pooling rebalanced: workgroups 0-63 (three scan items) now take 3 half-chunk pooling items each, workgroups 64-255 take 5 instead of 6
# speedup vs baseline: 1.0006x; 1.0006x over previous
.LBB0_482:
	v_readlane_b32 s4, v251, 0
	v_readlane_b32 s5, v251, 1
	s_load_dword s1, s[4:5], 0x10
	s_load_dword s6, s[4:5], 0x0
	v_readlane_b32 s34, v251, 10
	v_readlane_b32 s35, v251, 11
	s_waitcnt lgkmcnt(0)
	s_lshr_b32 s1, s1, 16
	s_cmp_lg_u32 s1, 0
	s_cselect_b64 s[4:5], -1, 0
	s_cmp_lg_u64 s[4:5], 0
	s_addc_u32 s1, s6, 0
	s_cmpk_eq_i32 s1, 0x100
	s_cselect_b64 s[4:5], -1, 0
	s_and_b64 s[6:7], s[4:5], exec
	s_cselect_b32 s18, s72, s2
	s_mov_b32 s100, 0x480
	s_mov_b32 s101, 0
	s_cmp_lg_u64 s[4:5], 0
	s_cbranch_scc0 .Lpl_bal_done
	s_movk_i32 s100, 0x3c0
	s_cmp_lt_i32 s72, 0
	s_cbranch_scc0 .Lpl_bal_done
	s_add_i32 s18, s2, 0x3c0
	s_mov_b32 s100, 0x480
	s_mov_b32 s101, 64
.Lpl_bal_done:
	s_cmpk_gt_u32 s18, 0x47f
	s_cbranch_scc1 .LBB0_549
	s_and_b64 s[4:5], s[4:5], exec
	s_cselect_b32 s19, 0xc0, s1
	s_cmp_lg_u32 s101, 0
	s_cselect_b32 s19, s101, s19
	s_ashr_i32 s1, s0, 31
	s_ashr_i32 s20, s30, 7
	s_lshl_b64 s[0:1], s[0:1], 1
	s_add_u32 s4, s28, s0
	s_addc_u32 s5, s29, s1
	s_add_u32 s0, s13, s0
	v_mov_b32_e32 v97, v151
	v_add_u32_e32 v10, s27, v96
	s_addc_u32 s1, s26, s1
	v_lshlrev_b32_e32 v0, 7, v122
	v_lshl_add_u64 v[6:7], s[4:5], 0, v[96:97]
	v_lshlrev_b32_e32 v11, 7, v99
	v_lshlrev_b32_e32 v12, 7, v118
	v_lshlrev_b32_e32 v13, 7, v119
	v_lshlrev_b32_e32 v14, 7, v120
	v_cmp_ne_u32_e64 s[40:41], 7, v99
	v_lshlrev_b32_e32 v15, 7, v121
	v_lshl_add_u32 v16, v123, 1, s27
	v_lshl_add_u64 v[8:9], s[0:1], 0, v[96:97]
	v_cmp_gt_u32_e64 s[42:43], 35, v121
	v_cmp_gt_u32_e64 s[44:45], 8, v123
	s_lshl_b32 s22, s18, 5
	s_lshl_b32 s23, s19, 5
	v_add_u32_e32 v17, v10, v0
	s_branch .LBB0_487

.LBB0_486:
	s_add_i32 s18, s18, s19
	s_add_i32 s22, s22, s23
	s_cmp_lt_i32 s18, s100
	s_cbranch_scc0 .LBB0_549
